# split grid barrier 4 plus hand-pipelined sample-row output projection item in the GLA-output phase
# speedup vs baseline: 1.0060x; 1.0060x over previous
; #define MFMA32(a, b, c) __builtin_amdgcn_mfma_f32_32x32x16_bf16((a), (b), (c), 0, 0, 0)
; DI void sample_out_item(const Params& p, int item, int lane) {
;     unsigned char* ws = p.ws;
;     const int qi = lane & 31, hh = lane >> 5, tg = item >> 5, nb = item & 31;
;     const int tok = T_P + 32 * tg + qi, wrow = wt_row(nb) + qi;
;     const bf16_t* up = (const bf16_t*)(ws + OFF_UB) + (size_t)tok * 1024 + 8 * hh;
;     const bf16_t* wp = (const bf16_t*)(ws + OFF_WOUT) + (size_t)wrow * 1024 + 8 * hh;
;     f32x16 acc;
; #pragma unroll
;     for (int r = 0; r < 16; ++r) acc[r] = 0.f;
; #pragma unroll 1
;     for (int c0 = 0; c0 < 64; c0 += 16) {
;         bf16x8 wa[16], ga[16];
; #pragma unroll
;         for (int j = 0; j < 16; ++j) { wa[j] = *(const bf16x8*)(wp + 16 * (c0 + j)); ga[j] = *(const bf16x8*)(up + 16 * (c0 + j)); }
;         __builtin_amdgcn_sched_barrier(0);
; #pragma unroll
;         for (int j = 0; j < 16; ++j) acc = MFMA32(wa[j], ga[j], acc);
.Lsb4b_done:
	s_bitcmp0_b32 s48, 3
	s_cbranch_scc0 .LBB0_1145
	s_ashr_i32 s10, s48, 1
	s_and_b32 s4, s10, -8
	s_and_b32 s11, s48, 7
	s_or_b32 s16, s4, s11
	s_cmpk_gt_i32 s16, 0x1ff
	s_cbranch_scc1 .LBB0_1145
	s_load_dwordx2 s[4:5], s[0:1], 0xc0
	s_load_dwordx2 s[8:9], s[0:1], 0x8
	s_add_u32 s18, s44, 0x1100000
	s_addc_u32 s19, s45, 0
	s_add_u32 s20, s44, 0x5700000
	s_addc_u32 s21, s45, 0
	v_and_b32_e32 v192, 31, v203
	v_bfe_u32 v193, v203, 5, 1
	s_lshr_b32 s10, s16, 5
	s_lshl_b32 s10, s10, 5
	s_and_b32 s11, s16, 31
	s_lshr_b32 s12, s11, 3
	s_lshl_b32 s12, s12, 8
	s_and_b32 s13, s11, 1
	s_lshl_b32 s13, s13, 7
	s_add_i32 s12, s12, s13
	s_bfe_u32 s13, s11, 0x20001
	s_lshl_b32 s13, s13, 5
	s_add_i32 s12, s12, s13
	s_lshl_b32 s11, s11, 7
	v_add_u32_e32 v198, s10, v192
	v_lshlrev_b32_e32 v196, 12, v198
	v_lshl_add_u32 v196, v193, 4, v196
	v_add_u32_e32 v196, s11, v196
	v_add_u32_e32 v197, 0x4000000, v196
	v_add_u32_e32 v198, 0x4000, v198
	v_lshlrev_b32_e32 v194, 11, v198
	v_lshl_add_u32 v194, v193, 4, v194
	v_add_u32_e32 v198, s12, v192
	v_lshlrev_b32_e32 v195, 11, v198
	v_lshl_add_u32 v195, v193, 4, v195
	s_waitcnt vmcnt(0) lgkmcnt(0)
	global_load_dwordx4 v[220:223], v196, s[8:9]
	global_load_dwordx4 v[224:227], v196, s[8:9] offset:32
	global_load_dwordx4 v[228:231], v196, s[8:9] offset:64
	global_load_dwordx4 v[232:235], v196, s[8:9] offset:96
	global_load_dwordx4 v[0:3], v195, s[18:19]
	global_load_dwordx4 v[4:7], v194, s[20:21]
	global_load_dwordx4 v[8:11], v195, s[18:19] offset:32
	global_load_dwordx4 v[12:15], v194, s[20:21] offset:32
	global_load_dwordx4 v[16:19], v195, s[18:19] offset:64
	global_load_dwordx4 v[20:23], v194, s[20:21] offset:64
	global_load_dwordx4 v[24:27], v195, s[18:19] offset:96
	global_load_dwordx4 v[28:31], v194, s[20:21] offset:96
	global_load_dwordx4 v[32:35], v195, s[18:19] offset:128
	global_load_dwordx4 v[36:39], v194, s[20:21] offset:128
	global_load_dwordx4 v[40:43], v195, s[18:19] offset:160
	global_load_dwordx4 v[44:47], v194, s[20:21] offset:160
	global_load_dwordx4 v[48:51], v195, s[18:19] offset:192
	global_load_dwordx4 v[52:55], v194, s[20:21] offset:192
	global_load_dwordx4 v[56:59], v195, s[18:19] offset:224
	global_load_dwordx4 v[60:63], v194, s[20:21] offset:224
	global_load_dwordx4 v[64:67], v195, s[18:19] offset:256
	global_load_dwordx4 v[68:71], v194, s[20:21] offset:256
	global_load_dwordx4 v[72:75], v195, s[18:19] offset:288
	global_load_dwordx4 v[76:79], v194, s[20:21] offset:288
	global_load_dwordx4 v[80:83], v195, s[18:19] offset:320
	global_load_dwordx4 v[84:87], v194, s[20:21] offset:320
	global_load_dwordx4 v[88:91], v195, s[18:19] offset:352
	global_load_dwordx4 v[92:95], v194, s[20:21] offset:352
	global_load_dwordx4 v[96:99], v195, s[18:19] offset:384
	global_load_dwordx4 v[100:103], v194, s[20:21] offset:384
	global_load_dwordx4 v[104:107], v195, s[18:19] offset:416
	global_load_dwordx4 v[108:111], v194, s[20:21] offset:416
	global_load_dwordx4 v[112:115], v195, s[18:19] offset:448
	global_load_dwordx4 v[116:119], v194, s[20:21] offset:448
	global_load_dwordx4 v[120:123], v195, s[18:19] offset:480
	global_load_dwordx4 v[124:127], v194, s[20:21] offset:480
	global_load_dwordx4 v[128:131], v195, s[18:19] offset:512
	global_load_dwordx4 v[132:135], v194, s[20:21] offset:512
	global_load_dwordx4 v[136:139], v195, s[18:19] offset:544
	global_load_dwordx4 v[140:143], v194, s[20:21] offset:544
	global_load_dwordx4 v[144:147], v195, s[18:19] offset:576
	global_load_dwordx4 v[148:151], v194, s[20:21] offset:576
	global_load_dwordx4 v[152:155], v195, s[18:19] offset:608
	global_load_dwordx4 v[156:159], v194, s[20:21] offset:608
	global_load_dwordx4 v[160:163], v195, s[18:19] offset:640
	global_load_dwordx4 v[164:167], v194, s[20:21] offset:640
	global_load_dwordx4 v[168:171], v195, s[18:19] offset:672
	global_load_dwordx4 v[172:175], v194, s[20:21] offset:672
	global_load_dwordx4 v[176:179], v195, s[18:19] offset:704
	global_load_dwordx4 v[180:183], v194, s[20:21] offset:704
	global_load_dwordx4 v[184:187], v195, s[18:19] offset:736
	global_load_dwordx4 v[188:191], v194, s[20:21] offset:736
	s_waitcnt vmcnt(32)
	v_mfma_f32_32x32x16_bf16 v[204:219], v[0:3], v[4:7], 0
	v_mfma_f32_32x32x16_bf16 v[204:219], v[8:11], v[12:15], v[204:219]
	v_mfma_f32_32x32x16_bf16 v[204:219], v[16:19], v[20:23], v[204:219]
	v_mfma_f32_32x32x16_bf16 v[204:219], v[24:27], v[28:31], v[204:219]
	v_mfma_f32_32x32x16_bf16 v[204:219], v[32:35], v[36:39], v[204:219]
	v_mfma_f32_32x32x16_bf16 v[204:219], v[40:43], v[44:47], v[204:219]
	v_mfma_f32_32x32x16_bf16 v[204:219], v[48:51], v[52:55], v[204:219]
	v_mfma_f32_32x32x16_bf16 v[204:219], v[56:59], v[60:63], v[204:219]
	global_load_dwordx4 v[0:3], v195, s[18:19] offset:768
	global_load_dwordx4 v[4:7], v194, s[20:21] offset:768
	global_load_dwordx4 v[8:11], v195, s[18:19] offset:800
	global_load_dwordx4 v[12:15], v194, s[20:21] offset:800
	global_load_dwordx4 v[16:19], v195, s[18:19] offset:832
	global_load_dwordx4 v[20:23], v194, s[20:21] offset:832
	global_load_dwordx4 v[24:27], v195, s[18:19] offset:864
	global_load_dwordx4 v[28:31], v194, s[20:21] offset:864
	global_load_dwordx4 v[32:35], v195, s[18:19] offset:896
	global_load_dwordx4 v[36:39], v194, s[20:21] offset:896
	global_load_dwordx4 v[40:43], v195, s[18:19] offset:928
	global_load_dwordx4 v[44:47], v194, s[20:21] offset:928
	global_load_dwordx4 v[48:51], v195, s[18:19] offset:960
	global_load_dwordx4 v[52:55], v194, s[20:21] offset:960
	global_load_dwordx4 v[56:59], v195, s[18:19] offset:992
	global_load_dwordx4 v[60:63], v194, s[20:21] offset:992
	s_waitcnt vmcnt(32)
; #define MFMA32(a, b, c) __builtin_amdgcn_mfma_f32_32x32x16_bf16((a), (b), (c), 0, 0, 0)
; DI void sample_out_item(const Params& p, int item, int lane) {
;     ...
; #pragma unroll 1
;     for (int c0 = 0; c0 < 64; c0 += 16) {
;         bf16x8 wa[16], ga[16];
; #pragma unroll
;         for (int j = 0; j < 16; ++j) { wa[j] = *(const bf16x8*)(wp + 16 * (c0 + j)); ga[j] = *(const bf16x8*)(up + 16 * (c0 + j)); }
;         __builtin_amdgcn_sched_barrier(0);
; #pragma unroll
;         for (int j = 0; j < 16; ++j) acc = MFMA32(wa[j], ga[j], acc);
;         __builtin_amdgcn_sched_barrier(0);
	v_mfma_f32_32x32x16_bf16 v[204:219], v[64:67], v[68:71], v[204:219]
	v_mfma_f32_32x32x16_bf16 v[204:219], v[72:75], v[76:79], v[204:219]
	v_mfma_f32_32x32x16_bf16 v[204:219], v[80:83], v[84:87], v[204:219]
	v_mfma_f32_32x32x16_bf16 v[204:219], v[88:91], v[92:95], v[204:219]
	v_mfma_f32_32x32x16_bf16 v[204:219], v[96:99], v[100:103], v[204:219]
	v_mfma_f32_32x32x16_bf16 v[204:219], v[104:107], v[108:111], v[204:219]
	v_mfma_f32_32x32x16_bf16 v[204:219], v[112:115], v[116:119], v[204:219]
	v_mfma_f32_32x32x16_bf16 v[204:219], v[120:123], v[124:127], v[204:219]
	global_load_dwordx4 v[64:67], v195, s[18:19] offset:1024
	global_load_dwordx4 v[68:71], v194, s[20:21] offset:1024
	global_load_dwordx4 v[72:75], v195, s[18:19] offset:1056
	global_load_dwordx4 v[76:79], v194, s[20:21] offset:1056
	global_load_dwordx4 v[80:83], v195, s[18:19] offset:1088
	global_load_dwordx4 v[84:87], v194, s[20:21] offset:1088
	global_load_dwordx4 v[88:91], v195, s[18:19] offset:1120
	global_load_dwordx4 v[92:95], v194, s[20:21] offset:1120
	global_load_dwordx4 v[96:99], v195, s[18:19] offset:1152
	global_load_dwordx4 v[100:103], v194, s[20:21] offset:1152
	global_load_dwordx4 v[104:107], v195, s[18:19] offset:1184
	global_load_dwordx4 v[108:111], v194, s[20:21] offset:1184
	global_load_dwordx4 v[112:115], v195, s[18:19] offset:1216
	global_load_dwordx4 v[116:119], v194, s[20:21] offset:1216
	global_load_dwordx4 v[120:123], v195, s[18:19] offset:1248
	global_load_dwordx4 v[124:127], v194, s[20:21] offset:1248
	s_waitcnt vmcnt(32)
	v_mfma_f32_32x32x16_bf16 v[204:219], v[128:131], v[132:135], v[204:219]
	v_mfma_f32_32x32x16_bf16 v[204:219], v[136:139], v[140:143], v[204:219]
	v_mfma_f32_32x32x16_bf16 v[204:219], v[144:147], v[148:151], v[204:219]
	v_mfma_f32_32x32x16_bf16 v[204:219], v[152:155], v[156:159], v[204:219]
	v_mfma_f32_32x32x16_bf16 v[204:219], v[160:163], v[164:167], v[204:219]
	v_mfma_f32_32x32x16_bf16 v[204:219], v[168:171], v[172:175], v[204:219]
	v_mfma_f32_32x32x16_bf16 v[204:219], v[176:179], v[180:183], v[204:219]
	v_mfma_f32_32x32x16_bf16 v[204:219], v[184:187], v[188:191], v[204:219]
	global_load_dwordx4 v[128:131], v195, s[18:19] offset:1280
	global_load_dwordx4 v[132:135], v194, s[20:21] offset:1280
	global_load_dwordx4 v[136:139], v195, s[18:19] offset:1312
	global_load_dwordx4 v[140:143], v194, s[20:21] offset:1312
	global_load_dwordx4 v[144:147], v195, s[18:19] offset:1344
	global_load_dwordx4 v[148:151], v194, s[20:21] offset:1344
	global_load_dwordx4 v[152:155], v195, s[18:19] offset:1376
	global_load_dwordx4 v[156:159], v194, s[20:21] offset:1376
	global_load_dwordx4 v[160:163], v195, s[18:19] offset:1408
	global_load_dwordx4 v[164:167], v194, s[20:21] offset:1408
	global_load_dwordx4 v[168:171], v195, s[18:19] offset:1440
	global_load_dwordx4 v[172:175], v194, s[20:21] offset:1440
	global_load_dwordx4 v[176:179], v195, s[18:19] offset:1472
	global_load_dwordx4 v[180:183], v194, s[20:21] offset:1472
	global_load_dwordx4 v[184:187], v195, s[18:19] offset:1504
	global_load_dwordx4 v[188:191], v194, s[20:21] offset:1504
	s_waitcnt vmcnt(32)
	v_mfma_f32_32x32x16_bf16 v[204:219], v[0:3], v[4:7], v[204:219]
	v_mfma_f32_32x32x16_bf16 v[204:219], v[8:11], v[12:15], v[204:219]
	v_mfma_f32_32x32x16_bf16 v[204:219], v[16:19], v[20:23], v[204:219]
	v_mfma_f32_32x32x16_bf16 v[204:219], v[24:27], v[28:31], v[204:219]
	v_mfma_f32_32x32x16_bf16 v[204:219], v[32:35], v[36:39], v[204:219]
	v_mfma_f32_32x32x16_bf16 v[204:219], v[40:43], v[44:47], v[204:219]
	v_mfma_f32_32x32x16_bf16 v[204:219], v[48:51], v[52:55], v[204:219]
	v_mfma_f32_32x32x16_bf16 v[204:219], v[56:59], v[60:63], v[204:219]
	global_load_dwordx4 v[0:3], v195, s[18:19] offset:1536
	global_load_dwordx4 v[4:7], v194, s[20:21] offset:1536
	global_load_dwordx4 v[8:11], v195, s[18:19] offset:1568
	global_load_dwordx4 v[12:15], v194, s[20:21] offset:1568
	global_load_dwordx4 v[16:19], v195, s[18:19] offset:1600
	global_load_dwordx4 v[20:23], v194, s[20:21] offset:1600
	global_load_dwordx4 v[24:27], v195, s[18:19] offset:1632
	global_load_dwordx4 v[28:31], v194, s[20:21] offset:1632
	global_load_dwordx4 v[32:35], v195, s[18:19] offset:1664
	global_load_dwordx4 v[36:39], v194, s[20:21] offset:1664
	global_load_dwordx4 v[40:43], v195, s[18:19] offset:1696
	global_load_dwordx4 v[44:47], v194, s[20:21] offset:1696
	global_load_dwordx4 v[48:51], v195, s[18:19] offset:1728
	global_load_dwordx4 v[52:55], v194, s[20:21] offset:1728
	global_load_dwordx4 v[56:59], v195, s[18:19] offset:1760
	global_load_dwordx4 v[60:63], v194, s[20:21] offset:1760
	s_waitcnt vmcnt(32)
; #define MFMA32(a, b, c) __builtin_amdgcn_mfma_f32_32x32x16_bf16((a), (b), (c), 0, 0, 0)
; DI void sample_out_item(const Params& p, int item, int lane) {
;     ...
;         __builtin_amdgcn_sched_barrier(0);
; #pragma unroll
;         for (int j = 0; j < 16; ++j) acc = MFMA32(wa[j], ga[j], acc);
;         __builtin_amdgcn_sched_barrier(0);
;     }
;     const float* xr = p.x_sample + (size_t)(tok - T_P) * 1024 + 32 * nb + 4 * hh;
;     float* yr = p.out + O_Y + (size_t)tok * 1024 + 32 * nb + 4 * hh;
; #pragma unroll
;     for (int g = 0; g < 4; ++g) { const f32x4 x = *(const f32x4*)(xr + 8 * g); f32x4 y; y[0] = x[0] + acc[4 * g]; y[1] = x[1] + acc[4 * g + 1]; y[2] = x[2] + acc[4 * g + 2]; y[3] = x[3] + acc[4 * g + 3]; *(f32x4*)(yr + 8 * g) = y; }
	v_mfma_f32_32x32x16_bf16 v[204:219], v[64:67], v[68:71], v[204:219]
	v_mfma_f32_32x32x16_bf16 v[204:219], v[72:75], v[76:79], v[204:219]
	v_mfma_f32_32x32x16_bf16 v[204:219], v[80:83], v[84:87], v[204:219]
	v_mfma_f32_32x32x16_bf16 v[204:219], v[88:91], v[92:95], v[204:219]
	v_mfma_f32_32x32x16_bf16 v[204:219], v[96:99], v[100:103], v[204:219]
	v_mfma_f32_32x32x16_bf16 v[204:219], v[104:107], v[108:111], v[204:219]
	v_mfma_f32_32x32x16_bf16 v[204:219], v[112:115], v[116:119], v[204:219]
	v_mfma_f32_32x32x16_bf16 v[204:219], v[120:123], v[124:127], v[204:219]
	global_load_dwordx4 v[64:67], v195, s[18:19] offset:1792
	global_load_dwordx4 v[68:71], v194, s[20:21] offset:1792
	global_load_dwordx4 v[72:75], v195, s[18:19] offset:1824
	global_load_dwordx4 v[76:79], v194, s[20:21] offset:1824
	global_load_dwordx4 v[80:83], v195, s[18:19] offset:1856
	global_load_dwordx4 v[84:87], v194, s[20:21] offset:1856
	global_load_dwordx4 v[88:91], v195, s[18:19] offset:1888
	global_load_dwordx4 v[92:95], v194, s[20:21] offset:1888
	global_load_dwordx4 v[96:99], v195, s[18:19] offset:1920
	global_load_dwordx4 v[100:103], v194, s[20:21] offset:1920
	global_load_dwordx4 v[104:107], v195, s[18:19] offset:1952
	global_load_dwordx4 v[108:111], v194, s[20:21] offset:1952
	global_load_dwordx4 v[112:115], v195, s[18:19] offset:1984
	global_load_dwordx4 v[116:119], v194, s[20:21] offset:1984
	global_load_dwordx4 v[120:123], v195, s[18:19] offset:2016
	global_load_dwordx4 v[124:127], v194, s[20:21] offset:2016
	s_waitcnt vmcnt(32)
	v_mfma_f32_32x32x16_bf16 v[204:219], v[128:131], v[132:135], v[204:219]
	v_mfma_f32_32x32x16_bf16 v[204:219], v[136:139], v[140:143], v[204:219]
	v_mfma_f32_32x32x16_bf16 v[204:219], v[144:147], v[148:151], v[204:219]
	v_mfma_f32_32x32x16_bf16 v[204:219], v[152:155], v[156:159], v[204:219]
	v_mfma_f32_32x32x16_bf16 v[204:219], v[160:163], v[164:167], v[204:219]
	v_mfma_f32_32x32x16_bf16 v[204:219], v[168:171], v[172:175], v[204:219]
	v_mfma_f32_32x32x16_bf16 v[204:219], v[176:179], v[180:183], v[204:219]
	v_mfma_f32_32x32x16_bf16 v[204:219], v[184:187], v[188:191], v[204:219]
	s_waitcnt vmcnt(16)
	v_mfma_f32_32x32x16_bf16 v[204:219], v[0:3], v[4:7], v[204:219]
	v_mfma_f32_32x32x16_bf16 v[204:219], v[8:11], v[12:15], v[204:219]
	v_mfma_f32_32x32x16_bf16 v[204:219], v[16:19], v[20:23], v[204:219]
	v_mfma_f32_32x32x16_bf16 v[204:219], v[24:27], v[28:31], v[204:219]
	v_mfma_f32_32x32x16_bf16 v[204:219], v[32:35], v[36:39], v[204:219]
	v_mfma_f32_32x32x16_bf16 v[204:219], v[40:43], v[44:47], v[204:219]
	v_mfma_f32_32x32x16_bf16 v[204:219], v[48:51], v[52:55], v[204:219]
	v_mfma_f32_32x32x16_bf16 v[204:219], v[56:59], v[60:63], v[204:219]
	s_waitcnt vmcnt(0)
	v_mfma_f32_32x32x16_bf16 v[204:219], v[64:67], v[68:71], v[204:219]
	v_mfma_f32_32x32x16_bf16 v[204:219], v[72:75], v[76:79], v[204:219]
	v_mfma_f32_32x32x16_bf16 v[204:219], v[80:83], v[84:87], v[204:219]
	v_mfma_f32_32x32x16_bf16 v[204:219], v[88:91], v[92:95], v[204:219]
	v_mfma_f32_32x32x16_bf16 v[204:219], v[96:99], v[100:103], v[204:219]
	v_mfma_f32_32x32x16_bf16 v[204:219], v[104:107], v[108:111], v[204:219]
	v_mfma_f32_32x32x16_bf16 v[204:219], v[112:115], v[116:119], v[204:219]
	v_mfma_f32_32x32x16_bf16 v[204:219], v[120:123], v[124:127], v[204:219]
	s_nop 7
	s_nop 3
	v_add_f32_e32 v220, v220, v204
	v_add_f32_e32 v221, v221, v205
	v_add_f32_e32 v222, v222, v206
	v_add_f32_e32 v223, v223, v207
	global_store_dwordx4 v197, v[220:223], s[4:5]
	v_add_f32_e32 v224, v224, v208
	v_add_f32_e32 v225, v225, v209
	v_add_f32_e32 v226, v226, v210
	v_add_f32_e32 v227, v227, v211
	global_store_dwordx4 v197, v[224:227], s[4:5] offset:32
	v_add_f32_e32 v228, v228, v212
	v_add_f32_e32 v229, v229, v213
	v_add_f32_e32 v230, v230, v214
	v_add_f32_e32 v231, v231, v215
	global_store_dwordx4 v197, v[228:231], s[4:5] offset:64
	v_add_f32_e32 v232, v232, v216
	v_add_f32_e32 v233, v233, v217
	v_add_f32_e32 v234, v234, v218
	v_add_f32_e32 v235, v235, v219
	global_store_dwordx4 v197, v[232:235], s[4:5] offset:96
